# glds gemm8 also for the proj GEMM (phase 2) and the out-proj split-K GEMM (phase 7); FFN-down stays on the register-staged loop
# speedup vs baseline: 1.1017x; 1.0215x over previous
.LBB0_189:
	s_cmp_lt_i32 s88, 3
	s_cselect_b64 s[18:19], -1, 0
	s_and_b64 s[4:5], s[18:19], s[4:5]
	s_andn2_b64 vcc, exec, s[4:5]
	s_cbranch_vccnz .LBB0_426
	s_add_u32 s16, s34, 0x28c4000
	s_addc_u32 s17, s35, 0
	s_add_u32 s6, s34, 0x8a44000
	s_addc_u32 s7, s35, 0
	s_add_u32 s8, s0, 0x120
	s_addc_u32 s9, s1, 0
	s_cmpk_lt_i32 s2, 0x100
	s_cbranch_scc0 .LBB0_197
	s_load_dword s9, s[0:1], 0x120
	v_readfirstlane_b32 s42, v205
	v_and_b32_e32 v192, 15, v204
	v_bfe_u32 v193, v204, 4, 2
	v_lshrrev_b32_e32 v194, 8, v204
	v_bfe_u32 v195, v204, 6, 2
	v_bfe_u32 v196, v204, 1, 3
	v_xor_b32_e32 v197, v193, v196
	v_xor_b32_e32 v198, 4, v197
	v_lshlrev_b32_e32 v197, 4, v197
	v_lshlrev_b32_e32 v198, 4, v198
	v_lshlrev_b32_e32 v199, 14, v194
	v_lshl_add_u32 v199, v192, 7, v199
	v_add_u32_e32 v242, v199, v197
	v_add_u32_e32 v243, v199, v198
	v_lshlrev_b32_e32 v199, 13, v195
	v_lshl_add_u32 v199, v192, 7, v199
	v_add_u32_e32 v199, 0x8000, v199
	v_add_u32_e32 v244, v199, v197
	v_add_u32_e32 v245, v199, v198
	v_add_u32_e32 v246, 0x10000, v242
	v_add_u32_e32 v248, 0x10000, v244
	v_add_u32_e32 v247, 0x10000, v243
	v_add_u32_e32 v249, 0x10000, v245
	v_lshrrev_b32_e32 v199, 3, v204
	v_and_b32_e32 v200, 7, v204
	v_bfe_u32 v201, v204, 4, 3
	v_xor_b32_e32 v200, v200, v201
	v_lshlrev_b32_e32 v200, 4, v200
	v_lshl_add_u32 v238, v199, 11, v200
	v_add_u32_e32 v239, 0x20000, v238
	v_add_u32_e32 v240, 0x40000, v238
	v_add_u32_e32 v241, 0x60000, v238
	s_lshl_b32 s42, s42, 10
	s_mov_b32 s8, s2
	s_and_b32 s44, s8, 7
	s_lshl_b32 s44, s44, 5
	s_lshr_b32 s45, s8, 3
	s_add_i32 s44, s44, s45
	s_lshr_b32 s45, s44, 6
	s_and_b32 s44, s44, 63
	s_and_b32 s98, s44, 7
	s_lshl_b32 s45, s45, 3
	s_add_i32 s45, s45, s98
	s_lshl_b32 s14, s45, 8
	s_lshr_b32 s44, s44, 3
	s_lshl_b32 s15, s44, 8
	s_mul_i32 s44, s14, 0x800
	s_add_u32 s44, s44, 0x8a44000
	s_add_u32 s10, s34, s44
	s_addc_u32 s11, s35, 0
	s_mul_i32 s44, s15, 0x800
	s_add_u32 s44, s44, 0x0
	s_add_u32 s12, s34, s44
	s_addc_u32 s13, s35, 0
	s_waitcnt vmcnt(0) lgkmcnt(0)
	s_barrier
	s_add_u32 m0, s42, 0x0
	s_nop 0
	global_load_lds_dwordx4 v238, s[10:11]
	s_add_u32 m0, s42, 0x2000
	s_nop 0
	global_load_lds_dwordx4 v239, s[10:11]
	s_add_u32 m0, s42, 0x4000
	s_nop 0
	global_load_lds_dwordx4 v240, s[10:11]
	s_add_u32 m0, s42, 0x6000
	s_nop 0
	global_load_lds_dwordx4 v241, s[10:11]
	s_add_u32 m0, s42, 0x8000
	s_nop 0
	global_load_lds_dwordx4 v238, s[12:13]
	s_add_u32 m0, s42, 0xa000
	s_nop 0
	global_load_lds_dwordx4 v239, s[12:13]
	s_add_u32 m0, s42, 0xc000
	s_nop 0
	global_load_lds_dwordx4 v240, s[12:13]
	s_add_u32 m0, s42, 0xe000
	s_nop 0
	global_load_lds_dwordx4 v241, s[12:13]
	s_waitcnt vmcnt(0)
.Lgl_tile_proj:
	s_add_i32 s43, s8, s9
	s_cmpk_lt_i32 s43, 256
	s_cselect_b64 s[26:27], 0, -1
	s_cbranch_scc0 .Lgl_nonext_proj
	s_and_b32 s44, s43, 7
	s_lshl_b32 s44, s44, 5
	s_lshr_b32 s45, s43, 3
	s_add_i32 s44, s44, s45
	s_lshr_b32 s45, s44, 6
	s_and_b32 s44, s44, 63
	s_and_b32 s98, s44, 7
	s_lshl_b32 s45, s45, 3
	s_add_i32 s45, s45, s98
	s_lshl_b32 s20, s45, 8
	s_lshr_b32 s44, s44, 3
	s_lshl_b32 s21, s44, 8
	s_mul_i32 s44, s20, 0x800
	s_add_u32 s44, s44, 0x8a44000
	s_add_u32 s22, s34, s44
	s_addc_u32 s23, s35, 0
	s_mul_i32 s44, s21, 0x800
	s_add_u32 s44, s44, 0x0
	s_add_u32 s24, s34, s44
	s_addc_u32 s25, s35, 0
	s_branch .Lgl_havenext_proj

.Lgl_havenext_proj:
	v_mov_b32_e32 v0, 0
	v_mov_b32_e32 v1, 0
	v_mov_b32_e32 v2, 0
	v_mov_b32_e32 v3, 0
	v_mov_b32_e32 v4, 0
	v_mov_b32_e32 v5, 0
	v_mov_b32_e32 v6, 0
	v_mov_b32_e32 v7, 0
	v_mov_b32_e32 v8, 0
	v_mov_b32_e32 v9, 0
	v_mov_b32_e32 v10, 0
	v_mov_b32_e32 v11, 0
	v_mov_b32_e32 v12, 0
	v_mov_b32_e32 v13, 0
	v_mov_b32_e32 v14, 0
	v_mov_b32_e32 v15, 0
	v_mov_b32_e32 v16, 0
	v_mov_b32_e32 v17, 0
	v_mov_b32_e32 v18, 0
	v_mov_b32_e32 v19, 0
	v_mov_b32_e32 v20, 0
	v_mov_b32_e32 v21, 0
	v_mov_b32_e32 v22, 0
	v_mov_b32_e32 v23, 0
	v_mov_b32_e32 v24, 0
	v_mov_b32_e32 v25, 0
	v_mov_b32_e32 v26, 0
	v_mov_b32_e32 v27, 0
	v_mov_b32_e32 v28, 0
	v_mov_b32_e32 v29, 0
	v_mov_b32_e32 v30, 0
	v_mov_b32_e32 v31, 0
	v_mov_b32_e32 v32, 0
	v_mov_b32_e32 v33, 0
	v_mov_b32_e32 v34, 0
	v_mov_b32_e32 v35, 0
	v_mov_b32_e32 v36, 0
	v_mov_b32_e32 v37, 0
	v_mov_b32_e32 v38, 0
	v_mov_b32_e32 v39, 0
	v_mov_b32_e32 v40, 0
	v_mov_b32_e32 v41, 0
	v_mov_b32_e32 v42, 0
	v_mov_b32_e32 v43, 0
	v_mov_b32_e32 v44, 0
	v_mov_b32_e32 v45, 0
	v_mov_b32_e32 v46, 0
	v_mov_b32_e32 v47, 0
	v_mov_b32_e32 v48, 0
	v_mov_b32_e32 v49, 0
	v_mov_b32_e32 v50, 0
	v_mov_b32_e32 v51, 0
	v_mov_b32_e32 v52, 0
	v_mov_b32_e32 v53, 0
	v_mov_b32_e32 v54, 0
	v_mov_b32_e32 v55, 0
	v_mov_b32_e32 v56, 0
	v_mov_b32_e32 v57, 0
	v_mov_b32_e32 v58, 0
	v_mov_b32_e32 v59, 0
	v_mov_b32_e32 v60, 0
	v_mov_b32_e32 v61, 0
	v_mov_b32_e32 v62, 0
	v_mov_b32_e32 v63, 0
	v_mov_b32_e32 v64, 0
	v_mov_b32_e32 v65, 0
	v_mov_b32_e32 v66, 0
	v_mov_b32_e32 v67, 0
	v_mov_b32_e32 v68, 0
	v_mov_b32_e32 v69, 0
	v_mov_b32_e32 v70, 0
	v_mov_b32_e32 v71, 0
	v_mov_b32_e32 v72, 0
	v_mov_b32_e32 v73, 0
	v_mov_b32_e32 v74, 0
	v_mov_b32_e32 v75, 0
	v_mov_b32_e32 v76, 0
	v_mov_b32_e32 v77, 0
	v_mov_b32_e32 v78, 0
	v_mov_b32_e32 v79, 0
	v_mov_b32_e32 v80, 0
	v_mov_b32_e32 v81, 0
	v_mov_b32_e32 v82, 0
	v_mov_b32_e32 v83, 0
	v_mov_b32_e32 v84, 0
	v_mov_b32_e32 v85, 0
	v_mov_b32_e32 v86, 0
	v_mov_b32_e32 v87, 0
	v_mov_b32_e32 v88, 0
	v_mov_b32_e32 v89, 0
	v_mov_b32_e32 v90, 0
	v_mov_b32_e32 v91, 0
	v_mov_b32_e32 v92, 0
	v_mov_b32_e32 v93, 0
	v_mov_b32_e32 v94, 0
	v_mov_b32_e32 v95, 0
	v_mov_b32_e32 v96, 0
	v_mov_b32_e32 v97, 0
	v_mov_b32_e32 v98, 0
	v_mov_b32_e32 v99, 0
	v_mov_b32_e32 v100, 0
	v_mov_b32_e32 v101, 0
	v_mov_b32_e32 v102, 0
	v_mov_b32_e32 v103, 0
	v_mov_b32_e32 v104, 0
	v_mov_b32_e32 v105, 0
	v_mov_b32_e32 v106, 0
	v_mov_b32_e32 v107, 0
	v_mov_b32_e32 v108, 0
	v_mov_b32_e32 v109, 0
	v_mov_b32_e32 v110, 0
	v_mov_b32_e32 v111, 0
	v_mov_b32_e32 v112, 0
	v_mov_b32_e32 v113, 0
	v_mov_b32_e32 v114, 0
	v_mov_b32_e32 v115, 0
	v_mov_b32_e32 v116, 0
	v_mov_b32_e32 v117, 0
	v_mov_b32_e32 v118, 0
	v_mov_b32_e32 v119, 0
	v_mov_b32_e32 v120, 0
	v_mov_b32_e32 v121, 0
	v_mov_b32_e32 v122, 0
	v_mov_b32_e32 v123, 0
	v_mov_b32_e32 v124, 0
	v_mov_b32_e32 v125, 0
	v_mov_b32_e32 v126, 0
	v_mov_b32_e32 v127, 0
	v_mov_b32_e32 v184, 0
	v_mov_b32_e32 v185, 0
	v_mov_b32_e32 v186, 0
	v_mov_b32_e32 v187, 0
	v_mov_b32_e32 v188, 0
	v_mov_b32_e32 v189, 0
	v_mov_b32_e32 v190, 0
	v_mov_b32_e32 v191, 0
	v_mov_b32_e32 v222, 0
	v_mov_b32_e32 v223, 0
	v_mov_b32_e32 v224, 0
	v_mov_b32_e32 v225, 0
	v_mov_b32_e32 v226, 0
	v_mov_b32_e32 v227, 0
	v_mov_b32_e32 v228, 0
	v_mov_b32_e32 v229, 0
	v_mov_b32_e32 v230, 0
	v_mov_b32_e32 v231, 0
	v_mov_b32_e32 v232, 0
	v_mov_b32_e32 v233, 0
	v_mov_b32_e32 v234, 0
	v_mov_b32_e32 v235, 0
	v_mov_b32_e32 v236, 0
	v_mov_b32_e32 v237, 0
	s_add_u32 s28, s10, 0x80
	s_addc_u32 s29, s11, 0
	s_add_u32 s30, s12, 0x80
	s_addc_u32 s31, s13, 0
	s_mov_b32 s33, 0
	s_waitcnt vmcnt(16)
	s_barrier
	s_branch .Lgl_kentry_proj

.Lgl_kentry_proj:
	s_setprio 1
	ds_read_b128 v[206:209], v244
	ds_read_b128 v[210:213], v244 offset:2048
	ds_read_b128 v[214:217], v244 offset:4096
	ds_read_b128 v[218:221], v244 offset:6144
	ds_read_b128 v[128:131], v242
	ds_read_b128 v[132:135], v242 offset:2048
	ds_read_b128 v[136:139], v242 offset:4096
	ds_read_b128 v[140:143], v242 offset:6144
	ds_read_b128 v[144:147], v242 offset:8192
	ds_read_b128 v[148:151], v242 offset:10240
	ds_read_b128 v[152:155], v242 offset:12288
	ds_read_b128 v[156:159], v242 offset:14336
	v_mfma_f32_16x16x32_bf16 v[96:99], v[222:225], v[184:187], v[96:99]
	v_mfma_f32_16x16x32_bf16 v[100:103], v[226:229], v[184:187], v[100:103]
	v_mfma_f32_16x16x32_bf16 v[104:107], v[230:233], v[184:187], v[104:107]
	v_mfma_f32_16x16x32_bf16 v[108:111], v[234:237], v[184:187], v[108:111]
	v_mfma_f32_16x16x32_bf16 v[112:115], v[222:225], v[188:191], v[112:115]
	v_mfma_f32_16x16x32_bf16 v[116:119], v[226:229], v[188:191], v[116:119]
	v_mfma_f32_16x16x32_bf16 v[120:123], v[230:233], v[188:191], v[120:123]
	v_mfma_f32_16x16x32_bf16 v[124:127], v[234:237], v[188:191], v[124:127]
	s_waitcnt lgkmcnt(7)
	v_mfma_f32_16x16x32_bf16 v[0:3], v[206:209], v[128:131], v[0:3]
	v_mfma_f32_16x16x32_bf16 v[4:7], v[210:213], v[128:131], v[4:7]
	v_mfma_f32_16x16x32_bf16 v[8:11], v[214:217], v[128:131], v[8:11]
	v_mfma_f32_16x16x32_bf16 v[12:15], v[218:221], v[128:131], v[12:15]
	s_add_u32 m0, s42, 0x10000
	s_nop 0
	global_load_lds_dwordx4 v238, s[28:29]
	s_add_u32 m0, s42, 0x12000
	s_nop 0
	global_load_lds_dwordx4 v239, s[28:29]
	ds_read_b128 v[222:225], v245
	ds_read_b128 v[226:229], v245 offset:2048
	s_waitcnt lgkmcnt(8)
	v_mfma_f32_16x16x32_bf16 v[16:19], v[206:209], v[132:135], v[16:19]
	v_mfma_f32_16x16x32_bf16 v[20:23], v[210:213], v[132:135], v[20:23]
	v_mfma_f32_16x16x32_bf16 v[24:27], v[214:217], v[132:135], v[24:27]
	v_mfma_f32_16x16x32_bf16 v[28:31], v[218:221], v[132:135], v[28:31]
	s_add_u32 m0, s42, 0x14000
	s_nop 0
	global_load_lds_dwordx4 v240, s[28:29]
	s_add_u32 m0, s42, 0x16000
	s_nop 0
	global_load_lds_dwordx4 v241, s[28:29]
	ds_read_b128 v[230:233], v245 offset:4096
	ds_read_b128 v[234:237], v245 offset:6144
	s_waitcnt lgkmcnt(9)
	v_mfma_f32_16x16x32_bf16 v[32:35], v[206:209], v[136:139], v[32:35]
	v_mfma_f32_16x16x32_bf16 v[36:39], v[210:213], v[136:139], v[36:39]
	v_mfma_f32_16x16x32_bf16 v[40:43], v[214:217], v[136:139], v[40:43]
	v_mfma_f32_16x16x32_bf16 v[44:47], v[218:221], v[136:139], v[44:47]
	s_add_u32 m0, s42, 0x18000
	s_nop 0
	global_load_lds_dwordx4 v238, s[30:31]
	s_add_u32 m0, s42, 0x1a000
	s_nop 0
	global_load_lds_dwordx4 v239, s[30:31]
	ds_read_b128 v[160:163], v243
	ds_read_b128 v[164:167], v243 offset:2048
	s_waitcnt lgkmcnt(10)
	v_mfma_f32_16x16x32_bf16 v[48:51], v[206:209], v[140:143], v[48:51]
	v_mfma_f32_16x16x32_bf16 v[52:55], v[210:213], v[140:143], v[52:55]
	v_mfma_f32_16x16x32_bf16 v[56:59], v[214:217], v[140:143], v[56:59]
	v_mfma_f32_16x16x32_bf16 v[60:63], v[218:221], v[140:143], v[60:63]
	s_add_u32 m0, s42, 0x1c000
	s_nop 0
	global_load_lds_dwordx4 v240, s[30:31]
	s_add_u32 m0, s42, 0x1e000
	s_nop 0
	global_load_lds_dwordx4 v241, s[30:31]
	ds_read_b128 v[168:171], v243 offset:4096
	ds_read_b128 v[172:175], v243 offset:6144
	s_waitcnt lgkmcnt(11)
	v_mfma_f32_16x16x32_bf16 v[64:67], v[206:209], v[144:147], v[64:67]
	v_mfma_f32_16x16x32_bf16 v[68:71], v[210:213], v[144:147], v[68:71]
	v_mfma_f32_16x16x32_bf16 v[72:75], v[214:217], v[144:147], v[72:75]
	v_mfma_f32_16x16x32_bf16 v[76:79], v[218:221], v[144:147], v[76:79]
	ds_read_b128 v[176:179], v243 offset:8192
	ds_read_b128 v[180:183], v243 offset:10240
	s_waitcnt lgkmcnt(12)
	v_mfma_f32_16x16x32_bf16 v[80:83], v[206:209], v[148:151], v[80:83]
	v_mfma_f32_16x16x32_bf16 v[84:87], v[210:213], v[148:151], v[84:87]
	v_mfma_f32_16x16x32_bf16 v[88:91], v[214:217], v[148:151], v[88:91]
	v_mfma_f32_16x16x32_bf16 v[92:95], v[218:221], v[148:151], v[92:95]
	ds_read_b128 v[184:187], v243 offset:12288
	ds_read_b128 v[188:191], v243 offset:14336
	s_waitcnt lgkmcnt(13)
	v_mfma_f32_16x16x32_bf16 v[96:99], v[206:209], v[152:155], v[96:99]
	v_mfma_f32_16x16x32_bf16 v[100:103], v[210:213], v[152:155], v[100:103]
	v_mfma_f32_16x16x32_bf16 v[104:107], v[214:217], v[152:155], v[104:107]
	v_mfma_f32_16x16x32_bf16 v[108:111], v[218:221], v[152:155], v[108:111]
	s_waitcnt lgkmcnt(12)
	v_mfma_f32_16x16x32_bf16 v[112:115], v[206:209], v[156:159], v[112:115]
	v_mfma_f32_16x16x32_bf16 v[116:119], v[210:213], v[156:159], v[116:119]
	v_mfma_f32_16x16x32_bf16 v[120:123], v[214:217], v[156:159], v[120:123]
	v_mfma_f32_16x16x32_bf16 v[124:127], v[218:221], v[156:159], v[124:127]
	s_waitcnt lgkmcnt(7)
	v_mfma_f32_16x16x32_bf16 v[0:3], v[222:225], v[160:163], v[0:3]
	v_mfma_f32_16x16x32_bf16 v[4:7], v[226:229], v[160:163], v[4:7]
	v_mfma_f32_16x16x32_bf16 v[8:11], v[230:233], v[160:163], v[8:11]
	v_mfma_f32_16x16x32_bf16 v[12:15], v[234:237], v[160:163], v[12:15]
	s_waitcnt lgkmcnt(6)
	v_mfma_f32_16x16x32_bf16 v[16:19], v[222:225], v[164:167], v[16:19]
	v_mfma_f32_16x16x32_bf16 v[20:23], v[226:229], v[164:167], v[20:23]
	v_mfma_f32_16x16x32_bf16 v[24:27], v[230:233], v[164:167], v[24:27]
	v_mfma_f32_16x16x32_bf16 v[28:31], v[234:237], v[164:167], v[28:31]
	s_waitcnt lgkmcnt(5)
	v_mfma_f32_16x16x32_bf16 v[32:35], v[222:225], v[168:171], v[32:35]
	v_mfma_f32_16x16x32_bf16 v[36:39], v[226:229], v[168:171], v[36:39]
	v_mfma_f32_16x16x32_bf16 v[40:43], v[230:233], v[168:171], v[40:43]
	v_mfma_f32_16x16x32_bf16 v[44:47], v[234:237], v[168:171], v[44:47]
	s_waitcnt lgkmcnt(4)
	v_mfma_f32_16x16x32_bf16 v[48:51], v[222:225], v[172:175], v[48:51]
	v_mfma_f32_16x16x32_bf16 v[52:55], v[226:229], v[172:175], v[52:55]
	v_mfma_f32_16x16x32_bf16 v[56:59], v[230:233], v[172:175], v[56:59]
	v_mfma_f32_16x16x32_bf16 v[60:63], v[234:237], v[172:175], v[60:63]
	s_waitcnt lgkmcnt(3)
	v_mfma_f32_16x16x32_bf16 v[64:67], v[222:225], v[176:179], v[64:67]
	v_mfma_f32_16x16x32_bf16 v[68:71], v[226:229], v[176:179], v[68:71]
	v_mfma_f32_16x16x32_bf16 v[72:75], v[230:233], v[176:179], v[72:75]
	v_mfma_f32_16x16x32_bf16 v[76:79], v[234:237], v[176:179], v[76:79]
	s_waitcnt lgkmcnt(2)
	v_mfma_f32_16x16x32_bf16 v[80:83], v[222:225], v[180:183], v[80:83]
	v_mfma_f32_16x16x32_bf16 v[84:87], v[226:229], v[180:183], v[84:87]
	v_mfma_f32_16x16x32_bf16 v[88:91], v[230:233], v[180:183], v[88:91]
	v_mfma_f32_16x16x32_bf16 v[92:95], v[234:237], v[180:183], v[92:95]
	s_setprio 0
	s_waitcnt vmcnt(0) lgkmcnt(0)
	s_barrier
	s_add_u32 s28, s28, 0x80
	s_addc_u32 s29, s29, 0
	s_add_u32 s30, s30, 0x80
	s_addc_u32 s31, s31, 0
	s_cmp_eq_u32 s33, 7
	s_cselect_b32 s28, s22, s28
	s_cselect_b32 s29, s23, s29
	s_cselect_b32 s30, s24, s30
	s_cselect_b32 s31, s25, s31
	s_setprio 1
	ds_read_b128 v[206:209], v248
	ds_read_b128 v[210:213], v248 offset:2048
	ds_read_b128 v[214:217], v248 offset:4096
	ds_read_b128 v[218:221], v248 offset:6144
	ds_read_b128 v[128:131], v246
	ds_read_b128 v[132:135], v246 offset:2048
	ds_read_b128 v[136:139], v246 offset:4096
	ds_read_b128 v[140:143], v246 offset:6144
	ds_read_b128 v[144:147], v246 offset:8192
	ds_read_b128 v[148:151], v246 offset:10240
	ds_read_b128 v[152:155], v246 offset:12288
	ds_read_b128 v[156:159], v246 offset:14336
	v_mfma_f32_16x16x32_bf16 v[96:99], v[222:225], v[184:187], v[96:99]
	v_mfma_f32_16x16x32_bf16 v[100:103], v[226:229], v[184:187], v[100:103]
	v_mfma_f32_16x16x32_bf16 v[104:107], v[230:233], v[184:187], v[104:107]
	v_mfma_f32_16x16x32_bf16 v[108:111], v[234:237], v[184:187], v[108:111]
	v_mfma_f32_16x16x32_bf16 v[112:115], v[222:225], v[188:191], v[112:115]
	v_mfma_f32_16x16x32_bf16 v[116:119], v[226:229], v[188:191], v[116:119]
	v_mfma_f32_16x16x32_bf16 v[120:123], v[230:233], v[188:191], v[120:123]
	v_mfma_f32_16x16x32_bf16 v[124:127], v[234:237], v[188:191], v[124:127]
	s_waitcnt lgkmcnt(7)
	v_mfma_f32_16x16x32_bf16 v[0:3], v[206:209], v[128:131], v[0:3]
	v_mfma_f32_16x16x32_bf16 v[4:7], v[210:213], v[128:131], v[4:7]
	v_mfma_f32_16x16x32_bf16 v[8:11], v[214:217], v[128:131], v[8:11]
	v_mfma_f32_16x16x32_bf16 v[12:15], v[218:221], v[128:131], v[12:15]
	s_add_u32 m0, s42, 0x0
	s_nop 0
	global_load_lds_dwordx4 v238, s[28:29]
	s_add_u32 m0, s42, 0x2000
	s_nop 0
	global_load_lds_dwordx4 v239, s[28:29]
	ds_read_b128 v[222:225], v249
	ds_read_b128 v[226:229], v249 offset:2048
	s_waitcnt lgkmcnt(8)
	v_mfma_f32_16x16x32_bf16 v[16:19], v[206:209], v[132:135], v[16:19]
	v_mfma_f32_16x16x32_bf16 v[20:23], v[210:213], v[132:135], v[20:23]
	v_mfma_f32_16x16x32_bf16 v[24:27], v[214:217], v[132:135], v[24:27]
	v_mfma_f32_16x16x32_bf16 v[28:31], v[218:221], v[132:135], v[28:31]
	s_add_u32 m0, s42, 0x4000
	s_nop 0
	global_load_lds_dwordx4 v240, s[28:29]
	s_add_u32 m0, s42, 0x6000
	s_nop 0
	global_load_lds_dwordx4 v241, s[28:29]
	ds_read_b128 v[230:233], v249 offset:4096
	ds_read_b128 v[234:237], v249 offset:6144
	s_waitcnt lgkmcnt(9)
	v_mfma_f32_16x16x32_bf16 v[32:35], v[206:209], v[136:139], v[32:35]
	v_mfma_f32_16x16x32_bf16 v[36:39], v[210:213], v[136:139], v[36:39]
	v_mfma_f32_16x16x32_bf16 v[40:43], v[214:217], v[136:139], v[40:43]
	v_mfma_f32_16x16x32_bf16 v[44:47], v[218:221], v[136:139], v[44:47]
	s_add_u32 m0, s42, 0x8000
	s_nop 0
	global_load_lds_dwordx4 v238, s[30:31]
	s_add_u32 m0, s42, 0xa000
	s_nop 0
	global_load_lds_dwordx4 v239, s[30:31]
	ds_read_b128 v[160:163], v247
	ds_read_b128 v[164:167], v247 offset:2048
	s_waitcnt lgkmcnt(10)
	v_mfma_f32_16x16x32_bf16 v[48:51], v[206:209], v[140:143], v[48:51]
	v_mfma_f32_16x16x32_bf16 v[52:55], v[210:213], v[140:143], v[52:55]
	v_mfma_f32_16x16x32_bf16 v[56:59], v[214:217], v[140:143], v[56:59]
	v_mfma_f32_16x16x32_bf16 v[60:63], v[218:221], v[140:143], v[60:63]
	s_add_u32 m0, s42, 0xc000
	s_nop 0
	global_load_lds_dwordx4 v240, s[30:31]
	s_add_u32 m0, s42, 0xe000
	s_nop 0
	global_load_lds_dwordx4 v241, s[30:31]
	ds_read_b128 v[168:171], v247 offset:4096
	ds_read_b128 v[172:175], v247 offset:6144
	s_waitcnt lgkmcnt(11)
	v_mfma_f32_16x16x32_bf16 v[64:67], v[206:209], v[144:147], v[64:67]
	v_mfma_f32_16x16x32_bf16 v[68:71], v[210:213], v[144:147], v[68:71]
	v_mfma_f32_16x16x32_bf16 v[72:75], v[214:217], v[144:147], v[72:75]
	v_mfma_f32_16x16x32_bf16 v[76:79], v[218:221], v[144:147], v[76:79]
	ds_read_b128 v[176:179], v247 offset:8192
	ds_read_b128 v[180:183], v247 offset:10240
	s_waitcnt lgkmcnt(12)
	v_mfma_f32_16x16x32_bf16 v[80:83], v[206:209], v[148:151], v[80:83]
	v_mfma_f32_16x16x32_bf16 v[84:87], v[210:213], v[148:151], v[84:87]
	v_mfma_f32_16x16x32_bf16 v[88:91], v[214:217], v[148:151], v[88:91]
	v_mfma_f32_16x16x32_bf16 v[92:95], v[218:221], v[148:151], v[92:95]
	ds_read_b128 v[184:187], v247 offset:12288
	ds_read_b128 v[188:191], v247 offset:14336
	s_waitcnt lgkmcnt(13)
	v_mfma_f32_16x16x32_bf16 v[96:99], v[206:209], v[152:155], v[96:99]
	v_mfma_f32_16x16x32_bf16 v[100:103], v[210:213], v[152:155], v[100:103]
	v_mfma_f32_16x16x32_bf16 v[104:107], v[214:217], v[152:155], v[104:107]
	v_mfma_f32_16x16x32_bf16 v[108:111], v[218:221], v[152:155], v[108:111]
	s_waitcnt lgkmcnt(12)
	v_mfma_f32_16x16x32_bf16 v[112:115], v[206:209], v[156:159], v[112:115]
	v_mfma_f32_16x16x32_bf16 v[116:119], v[210:213], v[156:159], v[116:119]
	v_mfma_f32_16x16x32_bf16 v[120:123], v[214:217], v[156:159], v[120:123]
	v_mfma_f32_16x16x32_bf16 v[124:127], v[218:221], v[156:159], v[124:127]
	s_waitcnt lgkmcnt(7)
	v_mfma_f32_16x16x32_bf16 v[0:3], v[222:225], v[160:163], v[0:3]
	v_mfma_f32_16x16x32_bf16 v[4:7], v[226:229], v[160:163], v[4:7]
	v_mfma_f32_16x16x32_bf16 v[8:11], v[230:233], v[160:163], v[8:11]
	v_mfma_f32_16x16x32_bf16 v[12:15], v[234:237], v[160:163], v[12:15]
	s_waitcnt lgkmcnt(6)
	v_mfma_f32_16x16x32_bf16 v[16:19], v[222:225], v[164:167], v[16:19]
	v_mfma_f32_16x16x32_bf16 v[20:23], v[226:229], v[164:167], v[20:23]
	v_mfma_f32_16x16x32_bf16 v[24:27], v[230:233], v[164:167], v[24:27]
	v_mfma_f32_16x16x32_bf16 v[28:31], v[234:237], v[164:167], v[28:31]
	s_waitcnt lgkmcnt(5)
	v_mfma_f32_16x16x32_bf16 v[32:35], v[222:225], v[168:171], v[32:35]
	v_mfma_f32_16x16x32_bf16 v[36:39], v[226:229], v[168:171], v[36:39]
	v_mfma_f32_16x16x32_bf16 v[40:43], v[230:233], v[168:171], v[40:43]
	v_mfma_f32_16x16x32_bf16 v[44:47], v[234:237], v[168:171], v[44:47]
	s_waitcnt lgkmcnt(4)
	v_mfma_f32_16x16x32_bf16 v[48:51], v[222:225], v[172:175], v[48:51]
	v_mfma_f32_16x16x32_bf16 v[52:55], v[226:229], v[172:175], v[52:55]
	v_mfma_f32_16x16x32_bf16 v[56:59], v[230:233], v[172:175], v[56:59]
	v_mfma_f32_16x16x32_bf16 v[60:63], v[234:237], v[172:175], v[60:63]
	s_waitcnt lgkmcnt(3)
	v_mfma_f32_16x16x32_bf16 v[64:67], v[222:225], v[176:179], v[64:67]
	v_mfma_f32_16x16x32_bf16 v[68:71], v[226:229], v[176:179], v[68:71]
	v_mfma_f32_16x16x32_bf16 v[72:75], v[230:233], v[176:179], v[72:75]
	v_mfma_f32_16x16x32_bf16 v[76:79], v[234:237], v[176:179], v[76:79]
	s_waitcnt lgkmcnt(2)
	v_mfma_f32_16x16x32_bf16 v[80:83], v[222:225], v[180:183], v[80:83]
	v_mfma_f32_16x16x32_bf16 v[84:87], v[226:229], v[180:183], v[84:87]
	v_mfma_f32_16x16x32_bf16 v[88:91], v[230:233], v[180:183], v[88:91]
	v_mfma_f32_16x16x32_bf16 v[92:95], v[234:237], v[180:183], v[92:95]
	s_setprio 0
	s_waitcnt lgkmcnt(0)
	s_add_u32 s28, s28, 0x80
	s_addc_u32 s29, s29, 0
	s_add_u32 s30, s30, 0x80
	s_addc_u32 s31, s31, 0
	s_add_i32 s33, s33, 1
	s_cmp_lt_u32 s33, 8
	s_cbranch_scc1 .Lgl_ktop_proj
	v_mfma_f32_16x16x32_bf16 v[96:99], v[222:225], v[184:187], v[96:99]
	v_mfma_f32_16x16x32_bf16 v[100:103], v[226:229], v[184:187], v[100:103]
	v_mfma_f32_16x16x32_bf16 v[104:107], v[230:233], v[184:187], v[104:107]
	v_mfma_f32_16x16x32_bf16 v[108:111], v[234:237], v[184:187], v[108:111]
	v_mfma_f32_16x16x32_bf16 v[112:115], v[222:225], v[188:191], v[112:115]
	v_mfma_f32_16x16x32_bf16 v[116:119], v[226:229], v[188:191], v[116:119]
	v_mfma_f32_16x16x32_bf16 v[120:123], v[230:233], v[188:191], v[120:123]
	v_mfma_f32_16x16x32_bf16 v[124:127], v[234:237], v[188:191], v[124:127]
	s_and_b32 s98, s14, 0xffff
	s_mul_i32 s98, s98, 0x1040
	s_lshl_b32 s99, s15, 1
	s_add_u32 s98, s98, s99
	s_add_u32 s98, s98, 0x28c4000
	s_add_u32 s100, s34, s98
	s_addc_u32 s101, s35, 0
	v_and_b32_e32 v160, 15, v204
	v_lshrrev_b32_e32 v161, 8, v204
	v_lshl_add_u32 v160, v161, 7, v160
	v_mul_u32_u24_e32 v160, 0x1040, v160
	v_and_b32_e32 v161, 0xc0, v204
	v_lshl_add_u32 v160, v161, 1, v160
	v_bfe_u32 v161, v204, 4, 1
	v_lshl_add_u32 v160, v161, 5, v160
	v_bfe_u32 v161, v204, 5, 1
	v_lshl_add_u32 v160, v161, 4, v160
	s_nop 7
	s_nop 7
	v_cvt_pk_bf16_f32 v0, v0, v1
	v_cvt_pk_bf16_f32 v1, v2, v3
	v_cvt_pk_bf16_f32 v2, v4, v5
	v_cvt_pk_bf16_f32 v3, v6, v7
	v_cvt_pk_bf16_f32 v8, v8, v9
	v_cvt_pk_bf16_f32 v9, v10, v11
	v_cvt_pk_bf16_f32 v10, v12, v13
	v_cvt_pk_bf16_f32 v11, v14, v15
	s_nop 1
	v_permlane16_swap_b32_e32 v0, v2
	v_permlane16_swap_b32_e32 v1, v3
	v_permlane16_swap_b32_e32 v8, v10
	v_permlane16_swap_b32_e32 v9, v11
	global_store_dwordx4 v160, v[0:3], s[100:101] sc1
	global_store_dwordx4 v160, v[8:11], s[100:101] offset:64 sc1
	s_add_u32 s100, s100, 0x10400
	s_addc_u32 s101, s101, 0
	v_cvt_pk_bf16_f32 v16, v16, v17
	v_cvt_pk_bf16_f32 v17, v18, v19
	v_cvt_pk_bf16_f32 v18, v20, v21
	v_cvt_pk_bf16_f32 v19, v22, v23
	v_cvt_pk_bf16_f32 v24, v24, v25
	v_cvt_pk_bf16_f32 v25, v26, v27
	v_cvt_pk_bf16_f32 v26, v28, v29
	v_cvt_pk_bf16_f32 v27, v30, v31
	s_nop 1
	v_permlane16_swap_b32_e32 v16, v18
	v_permlane16_swap_b32_e32 v17, v19
	v_permlane16_swap_b32_e32 v24, v26
	v_permlane16_swap_b32_e32 v25, v27
	global_store_dwordx4 v160, v[16:19], s[100:101] sc1
	global_store_dwordx4 v160, v[24:27], s[100:101] offset:64 sc1
	s_add_u32 s100, s100, 0x10400
	s_addc_u32 s101, s101, 0
	v_cvt_pk_bf16_f32 v32, v32, v33
	v_cvt_pk_bf16_f32 v33, v34, v35
	v_cvt_pk_bf16_f32 v34, v36, v37
	v_cvt_pk_bf16_f32 v35, v38, v39
	v_cvt_pk_bf16_f32 v40, v40, v41
	v_cvt_pk_bf16_f32 v41, v42, v43
	v_cvt_pk_bf16_f32 v42, v44, v45
	v_cvt_pk_bf16_f32 v43, v46, v47
	s_nop 1
	v_permlane16_swap_b32_e32 v32, v34
	v_permlane16_swap_b32_e32 v33, v35
	v_permlane16_swap_b32_e32 v40, v42
	v_permlane16_swap_b32_e32 v41, v43
	global_store_dwordx4 v160, v[32:35], s[100:101] sc1
	global_store_dwordx4 v160, v[40:43], s[100:101] offset:64 sc1
	s_add_u32 s100, s100, 0x10400
	s_addc_u32 s101, s101, 0
	v_cvt_pk_bf16_f32 v48, v48, v49
	v_cvt_pk_bf16_f32 v49, v50, v51
	v_cvt_pk_bf16_f32 v50, v52, v53
	v_cvt_pk_bf16_f32 v51, v54, v55
	v_cvt_pk_bf16_f32 v56, v56, v57
	v_cvt_pk_bf16_f32 v57, v58, v59
	v_cvt_pk_bf16_f32 v58, v60, v61
	v_cvt_pk_bf16_f32 v59, v62, v63
	s_nop 1
	v_permlane16_swap_b32_e32 v48, v50
	v_permlane16_swap_b32_e32 v49, v51
	v_permlane16_swap_b32_e32 v56, v58
	v_permlane16_swap_b32_e32 v57, v59
	global_store_dwordx4 v160, v[48:51], s[100:101] sc1
	global_store_dwordx4 v160, v[56:59], s[100:101] offset:64 sc1
	s_add_u32 s100, s100, 0x10400
	s_addc_u32 s101, s101, 0
	v_cvt_pk_bf16_f32 v64, v64, v65
	v_cvt_pk_bf16_f32 v65, v66, v67
	v_cvt_pk_bf16_f32 v66, v68, v69
	v_cvt_pk_bf16_f32 v67, v70, v71
	v_cvt_pk_bf16_f32 v72, v72, v73
	v_cvt_pk_bf16_f32 v73, v74, v75
	v_cvt_pk_bf16_f32 v74, v76, v77
	v_cvt_pk_bf16_f32 v75, v78, v79
	s_nop 1
	v_permlane16_swap_b32_e32 v64, v66
	v_permlane16_swap_b32_e32 v65, v67
	v_permlane16_swap_b32_e32 v72, v74
	v_permlane16_swap_b32_e32 v73, v75
	global_store_dwordx4 v160, v[64:67], s[100:101] sc1
	global_store_dwordx4 v160, v[72:75], s[100:101] offset:64 sc1
	s_add_u32 s100, s100, 0x10400
	s_addc_u32 s101, s101, 0
	v_cvt_pk_bf16_f32 v80, v80, v81
	v_cvt_pk_bf16_f32 v81, v82, v83
	v_cvt_pk_bf16_f32 v82, v84, v85
	v_cvt_pk_bf16_f32 v83, v86, v87
	v_cvt_pk_bf16_f32 v88, v88, v89
	v_cvt_pk_bf16_f32 v89, v90, v91
	v_cvt_pk_bf16_f32 v90, v92, v93
	v_cvt_pk_bf16_f32 v91, v94, v95
	s_nop 1
	v_permlane16_swap_b32_e32 v80, v82
	v_permlane16_swap_b32_e32 v81, v83
	v_permlane16_swap_b32_e32 v88, v90
	v_permlane16_swap_b32_e32 v89, v91
	global_store_dwordx4 v160, v[80:83], s[100:101] sc1
	global_store_dwordx4 v160, v[88:91], s[100:101] offset:64 sc1
	s_add_u32 s100, s100, 0x10400
	s_addc_u32 s101, s101, 0
	v_cvt_pk_bf16_f32 v96, v96, v97
	v_cvt_pk_bf16_f32 v97, v98, v99
	v_cvt_pk_bf16_f32 v98, v100, v101
	v_cvt_pk_bf16_f32 v99, v102, v103
	v_cvt_pk_bf16_f32 v104, v104, v105
	v_cvt_pk_bf16_f32 v105, v106, v107
	v_cvt_pk_bf16_f32 v106, v108, v109
	v_cvt_pk_bf16_f32 v107, v110, v111
	s_nop 1
	v_permlane16_swap_b32_e32 v96, v98
	v_permlane16_swap_b32_e32 v97, v99
	v_permlane16_swap_b32_e32 v104, v106
	v_permlane16_swap_b32_e32 v105, v107
	global_store_dwordx4 v160, v[96:99], s[100:101] sc1
	global_store_dwordx4 v160, v[104:107], s[100:101] offset:64 sc1
	s_add_u32 s100, s100, 0x10400
	s_addc_u32 s101, s101, 0
	v_cvt_pk_bf16_f32 v112, v112, v113
	v_cvt_pk_bf16_f32 v113, v114, v115
	v_cvt_pk_bf16_f32 v114, v116, v117
	v_cvt_pk_bf16_f32 v115, v118, v119
	v_cvt_pk_bf16_f32 v120, v120, v121
	v_cvt_pk_bf16_f32 v121, v122, v123
	v_cvt_pk_bf16_f32 v122, v124, v125
	v_cvt_pk_bf16_f32 v123, v126, v127
	s_nop 1
	v_permlane16_swap_b32_e32 v112, v114
	v_permlane16_swap_b32_e32 v113, v115
	v_permlane16_swap_b32_e32 v120, v122
	v_permlane16_swap_b32_e32 v121, v123
	global_store_dwordx4 v160, v[112:115], s[100:101] sc1
	global_store_dwordx4 v160, v[120:123], s[100:101] offset:64 sc1
	s_and_b64 vcc, exec, s[26:27]
	s_mov_b32 s14, s20
	s_mov_b32 s15, s21
	s_mov_b64 s[10:11], s[22:23]
	s_mov_b64 s[12:13], s[24:25]
	s_mov_b32 s8, s43
	s_cbranch_vccz .Lgl_tile_proj
	s_waitcnt vmcnt(0)
	s_barrier

.LBB0_1014:
	s_cmp_lt_i32 s88, 8
	s_cselect_b64 s[4:5], -1, 0
	s_and_b64 s[6:7], s[4:5], s[6:7]
	s_andn2_b64 vcc, exec, s[6:7]
	s_cbranch_vccnz .LBB0_1023
	s_cmpk_gt_i32 s2, 0xff
	s_cbranch_scc1 .LBB0_1023
	s_load_dword s9, s[0:1], 0x120
	v_readfirstlane_b32 s42, v205
	v_and_b32_e32 v192, 15, v204
	v_bfe_u32 v193, v204, 4, 2
	v_lshrrev_b32_e32 v194, 8, v204
	v_bfe_u32 v195, v204, 6, 2
	v_bfe_u32 v196, v204, 1, 3
	v_xor_b32_e32 v197, v193, v196
	v_xor_b32_e32 v198, 4, v197
	v_lshlrev_b32_e32 v197, 4, v197
	v_lshlrev_b32_e32 v198, 4, v198
	v_lshlrev_b32_e32 v199, 14, v194
	v_lshl_add_u32 v199, v192, 7, v199
	v_add_u32_e32 v242, v199, v197
	v_add_u32_e32 v243, v199, v198
	v_lshlrev_b32_e32 v199, 13, v195
	v_lshl_add_u32 v199, v192, 7, v199
	v_add_u32_e32 v199, 0x8000, v199
	v_add_u32_e32 v244, v199, v197
	v_add_u32_e32 v245, v199, v198
	v_add_u32_e32 v246, 0x10000, v242
	v_add_u32_e32 v248, 0x10000, v244
	v_add_u32_e32 v247, 0x10000, v243
	v_add_u32_e32 v249, 0x10000, v245
	v_lshrrev_b32_e32 v199, 3, v204
	v_and_b32_e32 v200, 7, v204
	v_bfe_u32 v201, v204, 4, 3
	v_xor_b32_e32 v200, v200, v201
	v_lshlrev_b32_e32 v200, 4, v200
	v_lshl_add_u32 v238, v199, 11, v200
	v_add_u32_e32 v239, 0x20000, v238
	v_add_u32_e32 v240, 0x40000, v238
	v_add_u32_e32 v241, 0x60000, v238
	s_lshl_b32 s42, s42, 10
	s_mov_b32 s8, s2
	s_and_b32 s44, s8, 7
	s_lshl_b32 s44, s44, 5
	s_lshr_b32 s45, s8, 3
	s_add_i32 s44, s44, s45
	s_lshr_b32 s45, s44, 7
	s_and_b32 s44, s44, 127
	s_and_b32 s98, s44, 3
	s_lshl_b32 s15, s98, 8
	s_lshr_b32 s44, s44, 2
	s_lshl_b32 s14, s44, 8
	s_mul_i32 s44, s14, 0x800
	s_mul_i32 s98, s45, 0x400
	s_add_u32 s44, s44, s98
	s_add_u32 s44, s44, 0x9a44000
	s_add_u32 s10, s34, s44
	s_addc_u32 s11, s35, 0
	s_mul_i32 s44, s15, 0x800
	s_add_u32 s44, s44, s98
	s_add_u32 s44, s44, 0x520000
	s_add_u32 s12, s34, s44
	s_addc_u32 s13, s35, 0
	s_lshl_b32 s45, s45, 16
	s_or_b32 s14, s14, s45
	s_waitcnt vmcnt(0) lgkmcnt(0)
	s_barrier
	s_add_u32 m0, s42, 0x0
	s_nop 0
	global_load_lds_dwordx4 v238, s[10:11]
	s_add_u32 m0, s42, 0x2000
	s_nop 0
	global_load_lds_dwordx4 v239, s[10:11]
	s_add_u32 m0, s42, 0x4000
	s_nop 0
	global_load_lds_dwordx4 v240, s[10:11]
	s_add_u32 m0, s42, 0x6000
	s_nop 0
	global_load_lds_dwordx4 v241, s[10:11]
	s_add_u32 m0, s42, 0x8000
	s_nop 0
	global_load_lds_dwordx4 v238, s[12:13]
	s_add_u32 m0, s42, 0xa000
	s_nop 0
	global_load_lds_dwordx4 v239, s[12:13]
	s_add_u32 m0, s42, 0xc000
	s_nop 0
	global_load_lds_dwordx4 v240, s[12:13]
	s_add_u32 m0, s42, 0xe000
	s_nop 0
	global_load_lds_dwordx4 v241, s[12:13]
	s_waitcnt vmcnt(0)
.Lgl_tile_outproj:
	s_add_i32 s43, s8, s9
	s_cmpk_lt_i32 s43, 256
	s_cselect_b64 s[26:27], 0, -1
	s_cbranch_scc0 .Lgl_nonext_outproj
	s_and_b32 s44, s43, 7
	s_lshl_b32 s44, s44, 5
	s_lshr_b32 s45, s43, 3
	s_add_i32 s44, s44, s45
	s_lshr_b32 s45, s44, 7
	s_and_b32 s44, s44, 127
	s_and_b32 s98, s44, 3
	s_lshl_b32 s21, s98, 8
	s_lshr_b32 s44, s44, 2
	s_lshl_b32 s20, s44, 8
	s_mul_i32 s44, s20, 0x800
	s_mul_i32 s98, s45, 0x400
	s_add_u32 s44, s44, s98
	s_add_u32 s44, s44, 0x9a44000
	s_add_u32 s22, s34, s44
	s_addc_u32 s23, s35, 0
	s_mul_i32 s44, s21, 0x800
	s_add_u32 s44, s44, s98
	s_add_u32 s44, s44, 0x520000
	s_add_u32 s24, s34, s44
	s_addc_u32 s25, s35, 0
	s_lshl_b32 s45, s45, 16
	s_or_b32 s20, s20, s45
	s_branch .Lgl_havenext_outproj

.Lgl_kentry_outproj:
	s_setprio 1
	ds_read_b128 v[206:209], v244
	ds_read_b128 v[210:213], v244 offset:2048
	ds_read_b128 v[214:217], v244 offset:4096
	ds_read_b128 v[218:221], v244 offset:6144
	ds_read_b128 v[128:131], v242
	ds_read_b128 v[132:135], v242 offset:2048
	ds_read_b128 v[136:139], v242 offset:4096
	ds_read_b128 v[140:143], v242 offset:6144
	ds_read_b128 v[144:147], v242 offset:8192
	ds_read_b128 v[148:151], v242 offset:10240
	ds_read_b128 v[152:155], v242 offset:12288
	ds_read_b128 v[156:159], v242 offset:14336
	v_mfma_f32_16x16x32_bf16 v[96:99], v[222:225], v[184:187], v[96:99]
	v_mfma_f32_16x16x32_bf16 v[100:103], v[226:229], v[184:187], v[100:103]
	v_mfma_f32_16x16x32_bf16 v[104:107], v[230:233], v[184:187], v[104:107]
	v_mfma_f32_16x16x32_bf16 v[108:111], v[234:237], v[184:187], v[108:111]
	v_mfma_f32_16x16x32_bf16 v[112:115], v[222:225], v[188:191], v[112:115]
	v_mfma_f32_16x16x32_bf16 v[116:119], v[226:229], v[188:191], v[116:119]
	v_mfma_f32_16x16x32_bf16 v[120:123], v[230:233], v[188:191], v[120:123]
	v_mfma_f32_16x16x32_bf16 v[124:127], v[234:237], v[188:191], v[124:127]
	s_waitcnt lgkmcnt(7)
	v_mfma_f32_16x16x32_bf16 v[0:3], v[206:209], v[128:131], v[0:3]
	v_mfma_f32_16x16x32_bf16 v[4:7], v[210:213], v[128:131], v[4:7]
	v_mfma_f32_16x16x32_bf16 v[8:11], v[214:217], v[128:131], v[8:11]
	v_mfma_f32_16x16x32_bf16 v[12:15], v[218:221], v[128:131], v[12:15]
	s_add_u32 m0, s42, 0x10000
	s_nop 0
	global_load_lds_dwordx4 v238, s[28:29]
	s_add_u32 m0, s42, 0x12000
	s_nop 0
	global_load_lds_dwordx4 v239, s[28:29]
	ds_read_b128 v[222:225], v245
	ds_read_b128 v[226:229], v245 offset:2048
	s_waitcnt lgkmcnt(8)
	v_mfma_f32_16x16x32_bf16 v[16:19], v[206:209], v[132:135], v[16:19]
	v_mfma_f32_16x16x32_bf16 v[20:23], v[210:213], v[132:135], v[20:23]
	v_mfma_f32_16x16x32_bf16 v[24:27], v[214:217], v[132:135], v[24:27]
	v_mfma_f32_16x16x32_bf16 v[28:31], v[218:221], v[132:135], v[28:31]
	s_add_u32 m0, s42, 0x14000
	s_nop 0
	global_load_lds_dwordx4 v240, s[28:29]
	s_add_u32 m0, s42, 0x16000
	s_nop 0
	global_load_lds_dwordx4 v241, s[28:29]
	ds_read_b128 v[230:233], v245 offset:4096
	ds_read_b128 v[234:237], v245 offset:6144
	s_waitcnt lgkmcnt(9)
	v_mfma_f32_16x16x32_bf16 v[32:35], v[206:209], v[136:139], v[32:35]
	v_mfma_f32_16x16x32_bf16 v[36:39], v[210:213], v[136:139], v[36:39]
	v_mfma_f32_16x16x32_bf16 v[40:43], v[214:217], v[136:139], v[40:43]
	v_mfma_f32_16x16x32_bf16 v[44:47], v[218:221], v[136:139], v[44:47]
	s_add_u32 m0, s42, 0x18000
	s_nop 0
	global_load_lds_dwordx4 v238, s[30:31]
	s_add_u32 m0, s42, 0x1a000
	s_nop 0
	global_load_lds_dwordx4 v239, s[30:31]
	ds_read_b128 v[160:163], v243
	ds_read_b128 v[164:167], v243 offset:2048
	s_waitcnt lgkmcnt(10)
	v_mfma_f32_16x16x32_bf16 v[48:51], v[206:209], v[140:143], v[48:51]
	v_mfma_f32_16x16x32_bf16 v[52:55], v[210:213], v[140:143], v[52:55]
	v_mfma_f32_16x16x32_bf16 v[56:59], v[214:217], v[140:143], v[56:59]
	v_mfma_f32_16x16x32_bf16 v[60:63], v[218:221], v[140:143], v[60:63]
	s_add_u32 m0, s42, 0x1c000
	s_nop 0
	global_load_lds_dwordx4 v240, s[30:31]
	s_add_u32 m0, s42, 0x1e000
	s_nop 0
	global_load_lds_dwordx4 v241, s[30:31]
	ds_read_b128 v[168:171], v243 offset:4096
	ds_read_b128 v[172:175], v243 offset:6144
	s_waitcnt lgkmcnt(11)
	v_mfma_f32_16x16x32_bf16 v[64:67], v[206:209], v[144:147], v[64:67]
	v_mfma_f32_16x16x32_bf16 v[68:71], v[210:213], v[144:147], v[68:71]
	v_mfma_f32_16x16x32_bf16 v[72:75], v[214:217], v[144:147], v[72:75]
	v_mfma_f32_16x16x32_bf16 v[76:79], v[218:221], v[144:147], v[76:79]
	ds_read_b128 v[176:179], v243 offset:8192
	ds_read_b128 v[180:183], v243 offset:10240
	s_waitcnt lgkmcnt(12)
	v_mfma_f32_16x16x32_bf16 v[80:83], v[206:209], v[148:151], v[80:83]
	v_mfma_f32_16x16x32_bf16 v[84:87], v[210:213], v[148:151], v[84:87]
	v_mfma_f32_16x16x32_bf16 v[88:91], v[214:217], v[148:151], v[88:91]
	v_mfma_f32_16x16x32_bf16 v[92:95], v[218:221], v[148:151], v[92:95]
	ds_read_b128 v[184:187], v243 offset:12288
	ds_read_b128 v[188:191], v243 offset:14336
	s_waitcnt lgkmcnt(13)
	v_mfma_f32_16x16x32_bf16 v[96:99], v[206:209], v[152:155], v[96:99]
	v_mfma_f32_16x16x32_bf16 v[100:103], v[210:213], v[152:155], v[100:103]
	v_mfma_f32_16x16x32_bf16 v[104:107], v[214:217], v[152:155], v[104:107]
	v_mfma_f32_16x16x32_bf16 v[108:111], v[218:221], v[152:155], v[108:111]
	s_waitcnt lgkmcnt(12)
	v_mfma_f32_16x16x32_bf16 v[112:115], v[206:209], v[156:159], v[112:115]
	v_mfma_f32_16x16x32_bf16 v[116:119], v[210:213], v[156:159], v[116:119]
	v_mfma_f32_16x16x32_bf16 v[120:123], v[214:217], v[156:159], v[120:123]
	v_mfma_f32_16x16x32_bf16 v[124:127], v[218:221], v[156:159], v[124:127]
	s_waitcnt lgkmcnt(7)
	v_mfma_f32_16x16x32_bf16 v[0:3], v[222:225], v[160:163], v[0:3]
	v_mfma_f32_16x16x32_bf16 v[4:7], v[226:229], v[160:163], v[4:7]
	v_mfma_f32_16x16x32_bf16 v[8:11], v[230:233], v[160:163], v[8:11]
	v_mfma_f32_16x16x32_bf16 v[12:15], v[234:237], v[160:163], v[12:15]
	s_waitcnt lgkmcnt(6)
	v_mfma_f32_16x16x32_bf16 v[16:19], v[222:225], v[164:167], v[16:19]
	v_mfma_f32_16x16x32_bf16 v[20:23], v[226:229], v[164:167], v[20:23]
	v_mfma_f32_16x16x32_bf16 v[24:27], v[230:233], v[164:167], v[24:27]
	v_mfma_f32_16x16x32_bf16 v[28:31], v[234:237], v[164:167], v[28:31]
	s_waitcnt lgkmcnt(5)
	v_mfma_f32_16x16x32_bf16 v[32:35], v[222:225], v[168:171], v[32:35]
	v_mfma_f32_16x16x32_bf16 v[36:39], v[226:229], v[168:171], v[36:39]
	v_mfma_f32_16x16x32_bf16 v[40:43], v[230:233], v[168:171], v[40:43]
	v_mfma_f32_16x16x32_bf16 v[44:47], v[234:237], v[168:171], v[44:47]
	s_waitcnt lgkmcnt(4)
	v_mfma_f32_16x16x32_bf16 v[48:51], v[222:225], v[172:175], v[48:51]
	v_mfma_f32_16x16x32_bf16 v[52:55], v[226:229], v[172:175], v[52:55]
	v_mfma_f32_16x16x32_bf16 v[56:59], v[230:233], v[172:175], v[56:59]
	v_mfma_f32_16x16x32_bf16 v[60:63], v[234:237], v[172:175], v[60:63]
	s_waitcnt lgkmcnt(3)
	v_mfma_f32_16x16x32_bf16 v[64:67], v[222:225], v[176:179], v[64:67]
	v_mfma_f32_16x16x32_bf16 v[68:71], v[226:229], v[176:179], v[68:71]
	v_mfma_f32_16x16x32_bf16 v[72:75], v[230:233], v[176:179], v[72:75]
	v_mfma_f32_16x16x32_bf16 v[76:79], v[234:237], v[176:179], v[76:79]
	s_waitcnt lgkmcnt(2)
	v_mfma_f32_16x16x32_bf16 v[80:83], v[222:225], v[180:183], v[80:83]
	v_mfma_f32_16x16x32_bf16 v[84:87], v[226:229], v[180:183], v[84:87]
	v_mfma_f32_16x16x32_bf16 v[88:91], v[230:233], v[180:183], v[88:91]
	v_mfma_f32_16x16x32_bf16 v[92:95], v[234:237], v[180:183], v[92:95]
	s_setprio 0
	s_waitcnt vmcnt(0) lgkmcnt(0)
	s_barrier
	s_add_u32 s28, s28, 0x80
	s_addc_u32 s29, s29, 0
	s_add_u32 s30, s30, 0x80
	s_addc_u32 s31, s31, 0
	s_cmp_eq_u32 s33, 3
	s_cselect_b32 s28, s22, s28
	s_cselect_b32 s29, s23, s29
	s_cselect_b32 s30, s24, s30
	s_cselect_b32 s31, s25, s31
	s_setprio 1
	ds_read_b128 v[206:209], v248
	ds_read_b128 v[210:213], v248 offset:2048
	ds_read_b128 v[214:217], v248 offset:4096
	ds_read_b128 v[218:221], v248 offset:6144
	ds_read_b128 v[128:131], v246
	ds_read_b128 v[132:135], v246 offset:2048
	ds_read_b128 v[136:139], v246 offset:4096
	ds_read_b128 v[140:143], v246 offset:6144
	ds_read_b128 v[144:147], v246 offset:8192
	ds_read_b128 v[148:151], v246 offset:10240
	ds_read_b128 v[152:155], v246 offset:12288
	ds_read_b128 v[156:159], v246 offset:14336
	v_mfma_f32_16x16x32_bf16 v[96:99], v[222:225], v[184:187], v[96:99]
	v_mfma_f32_16x16x32_bf16 v[100:103], v[226:229], v[184:187], v[100:103]
	v_mfma_f32_16x16x32_bf16 v[104:107], v[230:233], v[184:187], v[104:107]
	v_mfma_f32_16x16x32_bf16 v[108:111], v[234:237], v[184:187], v[108:111]
	v_mfma_f32_16x16x32_bf16 v[112:115], v[222:225], v[188:191], v[112:115]
	v_mfma_f32_16x16x32_bf16 v[116:119], v[226:229], v[188:191], v[116:119]
	v_mfma_f32_16x16x32_bf16 v[120:123], v[230:233], v[188:191], v[120:123]
	v_mfma_f32_16x16x32_bf16 v[124:127], v[234:237], v[188:191], v[124:127]
	s_waitcnt lgkmcnt(7)
	v_mfma_f32_16x16x32_bf16 v[0:3], v[206:209], v[128:131], v[0:3]
	v_mfma_f32_16x16x32_bf16 v[4:7], v[210:213], v[128:131], v[4:7]
	v_mfma_f32_16x16x32_bf16 v[8:11], v[214:217], v[128:131], v[8:11]
	v_mfma_f32_16x16x32_bf16 v[12:15], v[218:221], v[128:131], v[12:15]
	s_add_u32 m0, s42, 0x0
	s_nop 0
	global_load_lds_dwordx4 v238, s[28:29]
	s_add_u32 m0, s42, 0x2000
	s_nop 0
	global_load_lds_dwordx4 v239, s[28:29]
	ds_read_b128 v[222:225], v249
	ds_read_b128 v[226:229], v249 offset:2048
	s_waitcnt lgkmcnt(8)
	v_mfma_f32_16x16x32_bf16 v[16:19], v[206:209], v[132:135], v[16:19]
	v_mfma_f32_16x16x32_bf16 v[20:23], v[210:213], v[132:135], v[20:23]
	v_mfma_f32_16x16x32_bf16 v[24:27], v[214:217], v[132:135], v[24:27]
	v_mfma_f32_16x16x32_bf16 v[28:31], v[218:221], v[132:135], v[28:31]
	s_add_u32 m0, s42, 0x4000
	s_nop 0
	global_load_lds_dwordx4 v240, s[28:29]
	s_add_u32 m0, s42, 0x6000
	s_nop 0
	global_load_lds_dwordx4 v241, s[28:29]
	ds_read_b128 v[230:233], v249 offset:4096
	ds_read_b128 v[234:237], v249 offset:6144
	s_waitcnt lgkmcnt(9)
	v_mfma_f32_16x16x32_bf16 v[32:35], v[206:209], v[136:139], v[32:35]
	v_mfma_f32_16x16x32_bf16 v[36:39], v[210:213], v[136:139], v[36:39]
	v_mfma_f32_16x16x32_bf16 v[40:43], v[214:217], v[136:139], v[40:43]
	v_mfma_f32_16x16x32_bf16 v[44:47], v[218:221], v[136:139], v[44:47]
	s_add_u32 m0, s42, 0x8000
	s_nop 0
	global_load_lds_dwordx4 v238, s[30:31]
	s_add_u32 m0, s42, 0xa000
	s_nop 0
	global_load_lds_dwordx4 v239, s[30:31]
	ds_read_b128 v[160:163], v247
	ds_read_b128 v[164:167], v247 offset:2048
	s_waitcnt lgkmcnt(10)
	v_mfma_f32_16x16x32_bf16 v[48:51], v[206:209], v[140:143], v[48:51]
	v_mfma_f32_16x16x32_bf16 v[52:55], v[210:213], v[140:143], v[52:55]
	v_mfma_f32_16x16x32_bf16 v[56:59], v[214:217], v[140:143], v[56:59]
	v_mfma_f32_16x16x32_bf16 v[60:63], v[218:221], v[140:143], v[60:63]
	s_add_u32 m0, s42, 0xc000
	s_nop 0
	global_load_lds_dwordx4 v240, s[30:31]
	s_add_u32 m0, s42, 0xe000
	s_nop 0
	global_load_lds_dwordx4 v241, s[30:31]
	ds_read_b128 v[168:171], v247 offset:4096
	ds_read_b128 v[172:175], v247 offset:6144
	s_waitcnt lgkmcnt(11)
	v_mfma_f32_16x16x32_bf16 v[64:67], v[206:209], v[144:147], v[64:67]
	v_mfma_f32_16x16x32_bf16 v[68:71], v[210:213], v[144:147], v[68:71]
	v_mfma_f32_16x16x32_bf16 v[72:75], v[214:217], v[144:147], v[72:75]
	v_mfma_f32_16x16x32_bf16 v[76:79], v[218:221], v[144:147], v[76:79]
	ds_read_b128 v[176:179], v247 offset:8192
	ds_read_b128 v[180:183], v247 offset:10240
	s_waitcnt lgkmcnt(12)
	v_mfma_f32_16x16x32_bf16 v[80:83], v[206:209], v[148:151], v[80:83]
	v_mfma_f32_16x16x32_bf16 v[84:87], v[210:213], v[148:151], v[84:87]
	v_mfma_f32_16x16x32_bf16 v[88:91], v[214:217], v[148:151], v[88:91]
	v_mfma_f32_16x16x32_bf16 v[92:95], v[218:221], v[148:151], v[92:95]
	ds_read_b128 v[184:187], v247 offset:12288
	ds_read_b128 v[188:191], v247 offset:14336
	s_waitcnt lgkmcnt(13)
	v_mfma_f32_16x16x32_bf16 v[96:99], v[206:209], v[152:155], v[96:99]
	v_mfma_f32_16x16x32_bf16 v[100:103], v[210:213], v[152:155], v[100:103]
	v_mfma_f32_16x16x32_bf16 v[104:107], v[214:217], v[152:155], v[104:107]
	v_mfma_f32_16x16x32_bf16 v[108:111], v[218:221], v[152:155], v[108:111]
	s_waitcnt lgkmcnt(12)
	v_mfma_f32_16x16x32_bf16 v[112:115], v[206:209], v[156:159], v[112:115]
	v_mfma_f32_16x16x32_bf16 v[116:119], v[210:213], v[156:159], v[116:119]
	v_mfma_f32_16x16x32_bf16 v[120:123], v[214:217], v[156:159], v[120:123]
	v_mfma_f32_16x16x32_bf16 v[124:127], v[218:221], v[156:159], v[124:127]
	s_waitcnt lgkmcnt(7)
	v_mfma_f32_16x16x32_bf16 v[0:3], v[222:225], v[160:163], v[0:3]
	v_mfma_f32_16x16x32_bf16 v[4:7], v[226:229], v[160:163], v[4:7]
	v_mfma_f32_16x16x32_bf16 v[8:11], v[230:233], v[160:163], v[8:11]
	v_mfma_f32_16x16x32_bf16 v[12:15], v[234:237], v[160:163], v[12:15]
	s_waitcnt lgkmcnt(6)
	v_mfma_f32_16x16x32_bf16 v[16:19], v[222:225], v[164:167], v[16:19]
	v_mfma_f32_16x16x32_bf16 v[20:23], v[226:229], v[164:167], v[20:23]
	v_mfma_f32_16x16x32_bf16 v[24:27], v[230:233], v[164:167], v[24:27]
	v_mfma_f32_16x16x32_bf16 v[28:31], v[234:237], v[164:167], v[28:31]
	s_waitcnt lgkmcnt(5)
	v_mfma_f32_16x16x32_bf16 v[32:35], v[222:225], v[168:171], v[32:35]
	v_mfma_f32_16x16x32_bf16 v[36:39], v[226:229], v[168:171], v[36:39]
	v_mfma_f32_16x16x32_bf16 v[40:43], v[230:233], v[168:171], v[40:43]
	v_mfma_f32_16x16x32_bf16 v[44:47], v[234:237], v[168:171], v[44:47]
	s_waitcnt lgkmcnt(4)
	v_mfma_f32_16x16x32_bf16 v[48:51], v[222:225], v[172:175], v[48:51]
	v_mfma_f32_16x16x32_bf16 v[52:55], v[226:229], v[172:175], v[52:55]
	v_mfma_f32_16x16x32_bf16 v[56:59], v[230:233], v[172:175], v[56:59]
	v_mfma_f32_16x16x32_bf16 v[60:63], v[234:237], v[172:175], v[60:63]
	s_waitcnt lgkmcnt(3)
	v_mfma_f32_16x16x32_bf16 v[64:67], v[222:225], v[176:179], v[64:67]
	v_mfma_f32_16x16x32_bf16 v[68:71], v[226:229], v[176:179], v[68:71]
	v_mfma_f32_16x16x32_bf16 v[72:75], v[230:233], v[176:179], v[72:75]
	v_mfma_f32_16x16x32_bf16 v[76:79], v[234:237], v[176:179], v[76:79]
	s_waitcnt lgkmcnt(2)
	v_mfma_f32_16x16x32_bf16 v[80:83], v[222:225], v[180:183], v[80:83]
	v_mfma_f32_16x16x32_bf16 v[84:87], v[226:229], v[180:183], v[84:87]
	v_mfma_f32_16x16x32_bf16 v[88:91], v[230:233], v[180:183], v[88:91]
	v_mfma_f32_16x16x32_bf16 v[92:95], v[234:237], v[180:183], v[92:95]
	s_setprio 0
	s_waitcnt lgkmcnt(0)
	s_add_u32 s28, s28, 0x80
	s_addc_u32 s29, s29, 0
	s_add_u32 s30, s30, 0x80
	s_addc_u32 s31, s31, 0
	s_add_i32 s33, s33, 1
	s_cmp_lt_u32 s33, 4
	s_cbranch_scc1 .Lgl_ktop_outproj
	v_mfma_f32_16x16x32_bf16 v[96:99], v[222:225], v[184:187], v[96:99]
	v_mfma_f32_16x16x32_bf16 v[100:103], v[226:229], v[184:187], v[100:103]
	v_mfma_f32_16x16x32_bf16 v[104:107], v[230:233], v[184:187], v[104:107]
	v_mfma_f32_16x16x32_bf16 v[108:111], v[234:237], v[184:187], v[108:111]
	v_mfma_f32_16x16x32_bf16 v[112:115], v[222:225], v[188:191], v[112:115]
	v_mfma_f32_16x16x32_bf16 v[116:119], v[226:229], v[188:191], v[116:119]
	v_mfma_f32_16x16x32_bf16 v[120:123], v[230:233], v[188:191], v[120:123]
	v_mfma_f32_16x16x32_bf16 v[124:127], v[234:237], v[188:191], v[124:127]
	s_and_b32 s98, s14, 0xffff
	s_mul_i32 s98, s98, 0x800
	s_lshl_b32 s99, s15, 1
	s_add_u32 s98, s98, s99
	s_lshr_b32 s99, s14, 16
	s_cmp_eq_u32 s99, 0
	s_mov_b32 s99, 0x28c4000
	s_cselect_b32 s99, s99, 0x38c4000
	s_add_u32 s98, s98, s99
	s_add_u32 s100, s34, s98
	s_addc_u32 s101, s35, 0
	v_and_b32_e32 v160, 15, v204
	v_lshrrev_b32_e32 v161, 8, v204
	v_lshl_add_u32 v160, v161, 7, v160
	v_lshlrev_b32_e32 v160, 11, v160
	v_and_b32_e32 v161, 0xc0, v204
	v_lshl_add_u32 v160, v161, 1, v160
	v_bfe_u32 v161, v204, 4, 1
	v_lshl_add_u32 v160, v161, 5, v160
	v_bfe_u32 v161, v204, 5, 1
	v_lshl_add_u32 v160, v161, 4, v160
	s_nop 7
	s_nop 7
	v_cvt_pk_bf16_f32 v0, v0, v1
	v_cvt_pk_bf16_f32 v1, v2, v3
	v_cvt_pk_bf16_f32 v2, v4, v5
	v_cvt_pk_bf16_f32 v3, v6, v7
	v_cvt_pk_bf16_f32 v8, v8, v9
	v_cvt_pk_bf16_f32 v9, v10, v11
	v_cvt_pk_bf16_f32 v10, v12, v13
	v_cvt_pk_bf16_f32 v11, v14, v15
	s_nop 1
	v_permlane16_swap_b32_e32 v0, v2
	v_permlane16_swap_b32_e32 v1, v3
	v_permlane16_swap_b32_e32 v8, v10
	v_permlane16_swap_b32_e32 v9, v11
	global_store_dwordx4 v160, v[0:3], s[100:101] sc1
	global_store_dwordx4 v160, v[8:11], s[100:101] offset:64 sc1
	s_add_u32 s100, s100, 0x8000
	s_addc_u32 s101, s101, 0
	v_cvt_pk_bf16_f32 v16, v16, v17
	v_cvt_pk_bf16_f32 v17, v18, v19
	v_cvt_pk_bf16_f32 v18, v20, v21
	v_cvt_pk_bf16_f32 v19, v22, v23
	v_cvt_pk_bf16_f32 v24, v24, v25
	v_cvt_pk_bf16_f32 v25, v26, v27
	v_cvt_pk_bf16_f32 v26, v28, v29
	v_cvt_pk_bf16_f32 v27, v30, v31
	s_nop 1
	v_permlane16_swap_b32_e32 v16, v18
	v_permlane16_swap_b32_e32 v17, v19
	v_permlane16_swap_b32_e32 v24, v26
	v_permlane16_swap_b32_e32 v25, v27
	global_store_dwordx4 v160, v[16:19], s[100:101] sc1
	global_store_dwordx4 v160, v[24:27], s[100:101] offset:64 sc1
	s_add_u32 s100, s100, 0x8000
	s_addc_u32 s101, s101, 0
	v_cvt_pk_bf16_f32 v32, v32, v33
	v_cvt_pk_bf16_f32 v33, v34, v35
	v_cvt_pk_bf16_f32 v34, v36, v37
	v_cvt_pk_bf16_f32 v35, v38, v39
	v_cvt_pk_bf16_f32 v40, v40, v41
	v_cvt_pk_bf16_f32 v41, v42, v43
	v_cvt_pk_bf16_f32 v42, v44, v45
	v_cvt_pk_bf16_f32 v43, v46, v47
	s_nop 1
	v_permlane16_swap_b32_e32 v32, v34
	v_permlane16_swap_b32_e32 v33, v35
	v_permlane16_swap_b32_e32 v40, v42
	v_permlane16_swap_b32_e32 v41, v43
	global_store_dwordx4 v160, v[32:35], s[100:101] sc1
	global_store_dwordx4 v160, v[40:43], s[100:101] offset:64 sc1
	s_add_u32 s100, s100, 0x8000
	s_addc_u32 s101, s101, 0
	v_cvt_pk_bf16_f32 v48, v48, v49
	v_cvt_pk_bf16_f32 v49, v50, v51
	v_cvt_pk_bf16_f32 v50, v52, v53
	v_cvt_pk_bf16_f32 v51, v54, v55
	v_cvt_pk_bf16_f32 v56, v56, v57
	v_cvt_pk_bf16_f32 v57, v58, v59
	v_cvt_pk_bf16_f32 v58, v60, v61
	v_cvt_pk_bf16_f32 v59, v62, v63
	s_nop 1
	v_permlane16_swap_b32_e32 v48, v50
	v_permlane16_swap_b32_e32 v49, v51
	v_permlane16_swap_b32_e32 v56, v58
	v_permlane16_swap_b32_e32 v57, v59
	global_store_dwordx4 v160, v[48:51], s[100:101] sc1
	global_store_dwordx4 v160, v[56:59], s[100:101] offset:64 sc1
	s_add_u32 s100, s100, 0x8000
	s_addc_u32 s101, s101, 0
	v_cvt_pk_bf16_f32 v64, v64, v65
	v_cvt_pk_bf16_f32 v65, v66, v67
	v_cvt_pk_bf16_f32 v66, v68, v69
	v_cvt_pk_bf16_f32 v67, v70, v71
	v_cvt_pk_bf16_f32 v72, v72, v73
	v_cvt_pk_bf16_f32 v73, v74, v75
	v_cvt_pk_bf16_f32 v74, v76, v77
	v_cvt_pk_bf16_f32 v75, v78, v79
	s_nop 1
	v_permlane16_swap_b32_e32 v64, v66
	v_permlane16_swap_b32_e32 v65, v67
	v_permlane16_swap_b32_e32 v72, v74
	v_permlane16_swap_b32_e32 v73, v75
	global_store_dwordx4 v160, v[64:67], s[100:101] sc1
	global_store_dwordx4 v160, v[72:75], s[100:101] offset:64 sc1
	s_add_u32 s100, s100, 0x8000
	s_addc_u32 s101, s101, 0
	v_cvt_pk_bf16_f32 v80, v80, v81
	v_cvt_pk_bf16_f32 v81, v82, v83
	v_cvt_pk_bf16_f32 v82, v84, v85
	v_cvt_pk_bf16_f32 v83, v86, v87
	v_cvt_pk_bf16_f32 v88, v88, v89
	v_cvt_pk_bf16_f32 v89, v90, v91
	v_cvt_pk_bf16_f32 v90, v92, v93
	v_cvt_pk_bf16_f32 v91, v94, v95
	s_nop 1
	v_permlane16_swap_b32_e32 v80, v82
	v_permlane16_swap_b32_e32 v81, v83
	v_permlane16_swap_b32_e32 v88, v90
	v_permlane16_swap_b32_e32 v89, v91
	global_store_dwordx4 v160, v[80:83], s[100:101] sc1
	global_store_dwordx4 v160, v[88:91], s[100:101] offset:64 sc1
	s_add_u32 s100, s100, 0x8000
	s_addc_u32 s101, s101, 0
	v_cvt_pk_bf16_f32 v96, v96, v97
	v_cvt_pk_bf16_f32 v97, v98, v99
	v_cvt_pk_bf16_f32 v98, v100, v101
	v_cvt_pk_bf16_f32 v99, v102, v103
	v_cvt_pk_bf16_f32 v104, v104, v105
	v_cvt_pk_bf16_f32 v105, v106, v107
	v_cvt_pk_bf16_f32 v106, v108, v109
	v_cvt_pk_bf16_f32 v107, v110, v111
	s_nop 1
	v_permlane16_swap_b32_e32 v96, v98
	v_permlane16_swap_b32_e32 v97, v99
	v_permlane16_swap_b32_e32 v104, v106
	v_permlane16_swap_b32_e32 v105, v107
	global_store_dwordx4 v160, v[96:99], s[100:101] sc1
	global_store_dwordx4 v160, v[104:107], s[100:101] offset:64 sc1
	s_add_u32 s100, s100, 0x8000
	s_addc_u32 s101, s101, 0
	v_cvt_pk_bf16_f32 v112, v112, v113
	v_cvt_pk_bf16_f32 v113, v114, v115
	v_cvt_pk_bf16_f32 v114, v116, v117
	v_cvt_pk_bf16_f32 v115, v118, v119
	v_cvt_pk_bf16_f32 v120, v120, v121
	v_cvt_pk_bf16_f32 v121, v122, v123
	v_cvt_pk_bf16_f32 v122, v124, v125
	v_cvt_pk_bf16_f32 v123, v126, v127
	s_nop 1
	v_permlane16_swap_b32_e32 v112, v114
	v_permlane16_swap_b32_e32 v113, v115
	v_permlane16_swap_b32_e32 v120, v122
	v_permlane16_swap_b32_e32 v121, v123
	global_store_dwordx4 v160, v[112:115], s[100:101] sc1
	global_store_dwordx4 v160, v[120:123], s[100:101] offset:64 sc1
	s_and_b64 vcc, exec, s[26:27]
	s_mov_b32 s14, s20
	s_mov_b32 s15, s21
	s_mov_b64 s[10:11], s[22:23]
	s_mov_b64 s[12:13], s[24:25]
	s_mov_b32 s8, s43
	s_cbranch_vccz .Lgl_tile_outproj
	s_waitcnt vmcnt(0)
	s_barrier
	s_load_dwordx16 s[36:51], s[0:1], 0xc0
